# stack: attention wait fix + L0 out-proj wait removal + first-k-iteration vmcnt(N) + all 25 k-loops rotated
# speedup vs baseline: 1.0086x; 1.0070x over previous
; DEV int stage_next(int s) { return (s == 2 * GS_STAGE) ? 0 : s + GS_STAGE; }
; template <int WAIT0>
; DEV void gk_main(f32x16 (&acc)[2][2], const GTile& t, int s0) {
;     ...
;   vm_wait_bar<WAIT0>();
;   int stc = s0, std_ = stage_next(stage_next(s0));
; #pragma nounroll
;   for (int kt = 0; kt < nk - 2; ++kt) {
;     GK_DMA(std_, kt + 2);
;     GK_COMPUTE(stc);
;     vm_wait_bar<6>();
;     stc = stage_next(stc); std_ = stage_next(std_);
;   }
.Lfws_298:
	s_add_i32 s99, s0, 0
	v_add_u32_e32 v87, s99, v85
	ds_read_b128 v[88:91], v87
	ds_read_b128 v[92:95], v87 offset:4096
	v_add_u32_e32 v87, s99, v86
	ds_read_b128 v[96:99], v87 offset:16384
	ds_read_b128 v[100:103], v87 offset:20480
.LBB0_298:
	s_add_i32 s16, s1, s3
	s_mov_b32 s98, s16
	s_mov_b64 s[100:101], s[10:11]
	s_waitcnt lgkmcnt(0)
	v_add_u32_e32 v87, s99, v83
	ds_read_b128 v[236:239], v87
	ds_read_b128 v[240:243], v87 offset:4096
	v_add_u32_e32 v87, s99, v84
	ds_read_b128 v[244:247], v87 offset:16384
	ds_read_b128 v[248:251], v87 offset:20480
	v_mfma_f32_32x32x16_bf16 v[48:63], v[96:99], v[88:91], v[48:63]
	v_mfma_f32_32x32x16_bf16 v[32:47], v[96:99], v[92:95], v[32:47]
	s_mov_b32 m0, s98
	v_lshl_add_u64 v[254:255], v[76:77], 0, s[100:101]
	global_load_lds_dwordx4 v[254:255], off
	v_mfma_f32_32x32x16_bf16 v[16:31], v[100:103], v[88:91], v[16:31]
	v_mfma_f32_32x32x16_bf16 v[0:15], v[100:103], v[92:95], v[0:15]
	s_add_i32 m0, s98, 0x2000
	v_lshl_add_u64 v[254:255], v[74:75], 0, s[100:101]
	global_load_lds_dwordx4 v[254:255], off
	v_add_u32_e32 v87, s99, v81
	s_waitcnt lgkmcnt(0)
	ds_read_b128 v[88:91], v87
	ds_read_b128 v[92:95], v87 offset:4096
	v_add_u32_e32 v87, s99, v82
	ds_read_b128 v[96:99], v87 offset:16384
	ds_read_b128 v[100:103], v87 offset:20480
	v_mfma_f32_32x32x16_bf16 v[48:63], v[244:247], v[236:239], v[48:63]
	v_mfma_f32_32x32x16_bf16 v[32:47], v[244:247], v[240:243], v[32:47]
	s_add_i32 m0, s98, 0x4000
	v_lshl_add_u64 v[254:255], v[72:73], 0, s[100:101]
	global_load_lds_dwordx4 v[254:255], off
	v_mfma_f32_32x32x16_bf16 v[16:31], v[248:251], v[236:239], v[16:31]
	v_mfma_f32_32x32x16_bf16 v[0:15], v[248:251], v[240:243], v[0:15]
	s_add_i32 m0, s98, 0x6000
	v_lshl_add_u64 v[254:255], v[70:71], 0, s[100:101]
	global_load_lds_dwordx4 v[254:255], off
	v_add_u32_e32 v87, s99, v79
	s_waitcnt lgkmcnt(0)
	ds_read_b128 v[236:239], v87
	ds_read_b128 v[240:243], v87 offset:4096
	v_add_u32_e32 v87, s99, v80
	ds_read_b128 v[244:247], v87 offset:16384
	ds_read_b128 v[248:251], v87 offset:20480
	v_mfma_f32_32x32x16_bf16 v[48:63], v[96:99], v[88:91], v[48:63]
	v_mfma_f32_32x32x16_bf16 v[32:47], v[96:99], v[92:95], v[32:47]
	s_add_i32 m0, s98, 0x8000
	v_lshl_add_u64 v[254:255], v[68:69], 0, s[100:101]
	global_load_lds_dwordx4 v[254:255], off
	v_mfma_f32_32x32x16_bf16 v[16:31], v[100:103], v[88:91], v[16:31]
	v_mfma_f32_32x32x16_bf16 v[0:15], v[100:103], v[92:95], v[0:15]
	s_add_i32 m0, s98, 0xa000
	v_lshl_add_u64 v[254:255], v[66:67], 0, s[100:101]
	global_load_lds_dwordx4 v[254:255], off
	s_add_i32 s16, s0, 0xc000
	s_cmp_lg_u32 s0, 0x18000
	s_cselect_b32 s0, s16, 0
	s_add_i32 s16, s3, 0xc000
	s_waitcnt lgkmcnt(0)
	v_mfma_f32_32x32x16_bf16 v[48:63], v[244:247], v[236:239], v[48:63]
	s_cmp_lg_u32 s3, 0x18000
	s_cbranch_vccnz .Lfw_298
	s_waitcnt vmcnt(6) lgkmcnt(0)
	s_barrier
; DEV int stage_next(int s) { return (s == 2 * GS_STAGE) ? 0 : s + GS_STAGE; }
; template <int WAIT0>
; DEV void gk_main(f32x16 (&acc)[2][2], const GTile& t, int s0) {
;     ...
;   for (int kt = 0; kt < nk - 2; ++kt) {
;     GK_DMA(std_, kt + 2);
;     GK_COMPUTE(stc);
;     vm_wait_bar<6>();
;     stc = stage_next(stc); std_ = stage_next(std_);
;   }
;   GK_COMPUTE(stc);
;   vm_wait_bar<0>();
;   stc = stage_next(stc);
;   GK_COMPUTE(stc);
;   vm_wait_bar<0>();
.Lfwb_298:
	s_cselect_b32 s3, s16, 0
	s_add_u32 s10, s10, 0x80
	s_addc_u32 s11, s11, 0
	s_add_i32 s99, s0, 0
	v_add_u32_e32 v87, s99, v85
	ds_read_b128 v[88:91], v87
	ds_read_b128 v[92:95], v87 offset:4096
	v_add_u32_e32 v87, s99, v86
	ds_read_b128 v[96:99], v87 offset:16384
	ds_read_b128 v[100:103], v87 offset:20480
	v_mfma_f32_32x32x16_bf16 v[32:47], v[244:247], v[240:243], v[32:47]
	s_cmpk_lg_i32 s10, 0x700
	v_mfma_f32_32x32x16_bf16 v[16:31], v[248:251], v[236:239], v[16:31]
	v_mfma_f32_32x32x16_bf16 v[0:15], v[248:251], v[240:243], v[0:15]
	s_cbranch_scc1 .LBB0_298
	s_waitcnt lgkmcnt(0)
	s_add_i32 s1, s0, 0
	v_add_u32_e32 v87, s1, v86
	ds_read_b128 v[66:69], v87 offset:16384
	v_add_u32_e32 v74, s1, v85
	ds_read_b128 v[70:73], v74
	ds_read_b128 v[74:77], v74 offset:4096
	s_waitcnt lgkmcnt(0)
	v_mfma_f32_32x32x16_bf16 v[48:63], v[66:69], v[70:73], v[48:63]
	v_mfma_f32_32x32x16_bf16 v[32:47], v[66:69], v[74:77], v[32:47]
	ds_read_b128 v[66:69], v87 offset:20480
	v_add_u32_e32 v87, s1, v84
	s_waitcnt lgkmcnt(0)
	v_mfma_f32_32x32x16_bf16 v[16:31], v[66:69], v[70:73], v[16:31]
	v_mfma_f32_32x32x16_bf16 v[0:15], v[66:69], v[74:77], v[0:15]
	ds_read_b128 v[66:69], v87 offset:16384
	v_add_u32_e32 v74, s1, v83
	ds_read_b128 v[70:73], v74
	ds_read_b128 v[74:77], v74 offset:4096
	s_waitcnt lgkmcnt(0)
	v_mfma_f32_32x32x16_bf16 v[48:63], v[66:69], v[70:73], v[48:63]
	v_mfma_f32_32x32x16_bf16 v[32:47], v[66:69], v[74:77], v[32:47]
	ds_read_b128 v[66:69], v87 offset:20480
	v_add_u32_e32 v87, s1, v82
	s_waitcnt lgkmcnt(0)
	v_mfma_f32_32x32x16_bf16 v[16:31], v[66:69], v[70:73], v[16:31]
	v_mfma_f32_32x32x16_bf16 v[0:15], v[66:69], v[74:77], v[0:15]
	ds_read_b128 v[66:69], v87 offset:16384
	v_add_u32_e32 v74, s1, v81
	ds_read_b128 v[70:73], v74
	ds_read_b128 v[74:77], v74 offset:4096
	s_waitcnt lgkmcnt(0)
	v_mfma_f32_32x32x16_bf16 v[48:63], v[66:69], v[70:73], v[48:63]
	v_mfma_f32_32x32x16_bf16 v[32:47], v[66:69], v[74:77], v[32:47]
	ds_read_b128 v[66:69], v87 offset:20480
	v_add_u32_e32 v87, s1, v80
	s_waitcnt lgkmcnt(0)
	v_mfma_f32_32x32x16_bf16 v[16:31], v[66:69], v[70:73], v[16:31]
	v_mfma_f32_32x32x16_bf16 v[0:15], v[66:69], v[74:77], v[0:15]
	ds_read_b128 v[66:69], v87 offset:16384
	v_add_u32_e32 v74, s1, v79
	ds_read_b128 v[70:73], v74
	ds_read_b128 v[74:77], v74 offset:4096
	s_add_i32 s1, s0, 0xc000
	s_cmp_lg_u32 s0, 0x18000
	s_cselect_b32 s0, s1, 0
	s_waitcnt lgkmcnt(0)
	v_mfma_f32_32x32x16_bf16 v[48:63], v[66:69], v[70:73], v[48:63]
	s_add_i32 s0, s0, 0
	v_add_u32_e32 v86, s0, v86
	v_add_u32_e32 v84, s0, v84
	v_add_u32_e32 v82, s0, v82
	v_add_u32_e32 v80, s0, v80
	v_mfma_f32_32x32x16_bf16 v[32:47], v[66:69], v[74:77], v[32:47]
	ds_read_b128 v[66:69], v87 offset:20480
	s_waitcnt vmcnt(0) lgkmcnt(0)
	s_barrier
	s_waitcnt lgkmcnt(0)
	v_mfma_f32_32x32x16_bf16 v[16:31], v[66:69], v[70:73], v[16:31]
	v_mfma_f32_32x32x16_bf16 v[0:15], v[66:69], v[74:77], v[0:15]
	ds_read_b128 v[66:69], v86 offset:16384
	v_add_u32_e32 v74, s0, v85
	ds_read_b128 v[70:73], v74
	ds_read_b128 v[74:77], v74 offset:4096
	s_waitcnt lgkmcnt(0)
	v_mfma_f32_32x32x16_bf16 v[48:63], v[66:69], v[70:73], v[48:63]
	v_mfma_f32_32x32x16_bf16 v[32:47], v[66:69], v[74:77], v[32:47]
	ds_read_b128 v[66:69], v86 offset:20480
	s_waitcnt lgkmcnt(0)
	v_mfma_f32_32x32x16_bf16 v[16:31], v[66:69], v[70:73], v[16:31]
	v_mfma_f32_32x32x16_bf16 v[0:15], v[66:69], v[74:77], v[0:15]
	ds_read_b128 v[66:69], v84 offset:16384
	v_add_u32_e32 v74, s0, v83
	ds_read_b128 v[70:73], v74
	ds_read_b128 v[74:77], v74 offset:4096
	s_waitcnt lgkmcnt(0)
	v_mfma_f32_32x32x16_bf16 v[48:63], v[66:69], v[70:73], v[48:63]
	v_mfma_f32_32x32x16_bf16 v[32:47], v[66:69], v[74:77], v[32:47]
	ds_read_b128 v[66:69], v84 offset:20480
	s_waitcnt lgkmcnt(0)
	v_mfma_f32_32x32x16_bf16 v[16:31], v[66:69], v[70:73], v[16:31]
	v_mfma_f32_32x32x16_bf16 v[0:15], v[66:69], v[74:77], v[0:15]
	ds_read_b128 v[66:69], v82 offset:16384
	v_add_u32_e32 v74, s0, v81
	ds_read_b128 v[70:73], v74
	ds_read_b128 v[74:77], v74 offset:4096
	s_waitcnt lgkmcnt(0)
	v_mfma_f32_32x32x16_bf16 v[48:63], v[66:69], v[70:73], v[48:63]
	v_mfma_f32_32x32x16_bf16 v[32:47], v[66:69], v[74:77], v[32:47]
	ds_read_b128 v[66:69], v82 offset:20480
	s_waitcnt lgkmcnt(0)
	v_mfma_f32_32x32x16_bf16 v[16:31], v[66:69], v[70:73], v[16:31]
	v_mfma_f32_32x32x16_bf16 v[0:15], v[66:69], v[74:77], v[0:15]
	ds_read_b128 v[66:69], v80 offset:16384
	v_add_u32_e32 v74, s0, v79
	ds_read_b128 v[70:73], v74
	ds_read_b128 v[74:77], v74 offset:4096
	s_mov_b64 s[0:1], 0
	s_waitcnt lgkmcnt(0)
	v_mfma_f32_32x32x16_bf16 v[48:63], v[66:69], v[70:73], v[48:63]
	v_mfma_f32_32x32x16_bf16 v[32:47], v[66:69], v[74:77], v[32:47]
	ds_read_b128 v[66:69], v80 offset:20480
	s_waitcnt vmcnt(0) lgkmcnt(0)
	s_barrier
	s_waitcnt lgkmcnt(0)
	v_mfma_f32_32x32x16_bf16 v[16:31], v[66:69], v[70:73], v[16:31]
	v_mfma_f32_32x32x16_bf16 v[0:15], v[66:69], v[74:77], v[0:15]

; DEV int stage_next(int s) { return (s == 2 * GS_STAGE) ? 0 : s + GS_STAGE; }
; template <int WAIT0>
; DEV void gk_main(f32x16 (&acc)[2][2], const GTile& t, int s0) {
;     ...
;   for (int kt = 0; kt < nk - 2; ++kt) {
;     GK_DMA(std_, kt + 2);
;     GK_COMPUTE(stc);
;     vm_wait_bar<6>();
;     stc = stage_next(stc); std_ = stage_next(std_);
;   }
;   GK_COMPUTE(stc);
;   vm_wait_bar<0>();
;   stc = stage_next(stc);
;   GK_COMPUTE(stc);
;   vm_wait_bar<0>();
.Lfwb_302:
	s_cselect_b32 s3, s16, 0
	s_add_u32 s10, s10, 0x80
	s_addc_u32 s11, s11, 0
	s_add_i32 s99, s0, 0
	v_add_u32_e32 v87, s99, v85
	ds_read_b128 v[88:91], v87
	ds_read_b128 v[92:95], v87 offset:4096
	v_add_u32_e32 v87, s99, v86
	ds_read_b128 v[96:99], v87 offset:16384
	ds_read_b128 v[100:103], v87 offset:20480
	v_mfma_f32_32x32x16_bf16 v[32:47], v[244:247], v[240:243], v[32:47]
	s_cmpk_lg_i32 s10, 0x700
	v_mfma_f32_32x32x16_bf16 v[16:31], v[248:251], v[236:239], v[16:31]
	v_mfma_f32_32x32x16_bf16 v[0:15], v[248:251], v[240:243], v[0:15]
	s_cbranch_scc1 .LBB0_302
	s_waitcnt lgkmcnt(0)
	s_add_i32 s1, s0, 0
	v_add_u32_e32 v87, s1, v86
	ds_read_b128 v[66:69], v87 offset:16384
	v_add_u32_e32 v74, s1, v85
	ds_read_b128 v[70:73], v74
	ds_read_b128 v[74:77], v74 offset:4096
	s_waitcnt lgkmcnt(0)
	v_mfma_f32_32x32x16_bf16 v[48:63], v[66:69], v[70:73], v[48:63]
	v_mfma_f32_32x32x16_bf16 v[32:47], v[66:69], v[74:77], v[32:47]
	ds_read_b128 v[66:69], v87 offset:20480
	v_add_u32_e32 v87, s1, v84
	s_waitcnt lgkmcnt(0)
	v_mfma_f32_32x32x16_bf16 v[16:31], v[66:69], v[70:73], v[16:31]
	v_mfma_f32_32x32x16_bf16 v[0:15], v[66:69], v[74:77], v[0:15]
	ds_read_b128 v[66:69], v87 offset:16384
	v_add_u32_e32 v74, s1, v83
	ds_read_b128 v[70:73], v74
	ds_read_b128 v[74:77], v74 offset:4096
	s_waitcnt lgkmcnt(0)
	v_mfma_f32_32x32x16_bf16 v[48:63], v[66:69], v[70:73], v[48:63]
	v_mfma_f32_32x32x16_bf16 v[32:47], v[66:69], v[74:77], v[32:47]
	ds_read_b128 v[66:69], v87 offset:20480
	v_add_u32_e32 v87, s1, v82
	s_waitcnt lgkmcnt(0)
	v_mfma_f32_32x32x16_bf16 v[16:31], v[66:69], v[70:73], v[16:31]
	v_mfma_f32_32x32x16_bf16 v[0:15], v[66:69], v[74:77], v[0:15]
	ds_read_b128 v[66:69], v87 offset:16384
	v_add_u32_e32 v74, s1, v81
	ds_read_b128 v[70:73], v74
	ds_read_b128 v[74:77], v74 offset:4096
	s_waitcnt lgkmcnt(0)
	v_mfma_f32_32x32x16_bf16 v[48:63], v[66:69], v[70:73], v[48:63]
	v_mfma_f32_32x32x16_bf16 v[32:47], v[66:69], v[74:77], v[32:47]
	ds_read_b128 v[66:69], v87 offset:20480
	v_add_u32_e32 v87, s1, v80
	s_waitcnt lgkmcnt(0)
	v_mfma_f32_32x32x16_bf16 v[16:31], v[66:69], v[70:73], v[16:31]
	v_mfma_f32_32x32x16_bf16 v[0:15], v[66:69], v[74:77], v[0:15]
	ds_read_b128 v[66:69], v87 offset:16384
	v_add_u32_e32 v74, s1, v79
	ds_read_b128 v[70:73], v74
	ds_read_b128 v[74:77], v74 offset:4096
	s_add_i32 s1, s0, 0xc000
	s_cmp_lg_u32 s0, 0x18000
	s_cselect_b32 s0, s1, 0
	s_waitcnt lgkmcnt(0)
	v_mfma_f32_32x32x16_bf16 v[48:63], v[66:69], v[70:73], v[48:63]
	s_add_i32 s0, s0, 0
	v_add_u32_e32 v86, s0, v86
	v_add_u32_e32 v84, s0, v84
	v_add_u32_e32 v82, s0, v82
	v_add_u32_e32 v80, s0, v80
	v_mfma_f32_32x32x16_bf16 v[32:47], v[66:69], v[74:77], v[32:47]
	ds_read_b128 v[66:69], v87 offset:20480
	s_waitcnt vmcnt(0) lgkmcnt(0)
	s_barrier
	s_waitcnt lgkmcnt(0)
	v_mfma_f32_32x32x16_bf16 v[16:31], v[66:69], v[70:73], v[16:31]
	v_mfma_f32_32x32x16_bf16 v[0:15], v[66:69], v[74:77], v[0:15]
	ds_read_b128 v[66:69], v86 offset:16384
	v_add_u32_e32 v74, s0, v85
	ds_read_b128 v[70:73], v74
	ds_read_b128 v[74:77], v74 offset:4096
	s_waitcnt lgkmcnt(0)
	v_mfma_f32_32x32x16_bf16 v[48:63], v[66:69], v[70:73], v[48:63]
	v_mfma_f32_32x32x16_bf16 v[32:47], v[66:69], v[74:77], v[32:47]
	ds_read_b128 v[66:69], v86 offset:20480
	s_waitcnt lgkmcnt(0)
	v_mfma_f32_32x32x16_bf16 v[16:31], v[66:69], v[70:73], v[16:31]
	v_mfma_f32_32x32x16_bf16 v[0:15], v[66:69], v[74:77], v[0:15]
	ds_read_b128 v[66:69], v84 offset:16384
	v_add_u32_e32 v74, s0, v83
	ds_read_b128 v[70:73], v74
	ds_read_b128 v[74:77], v74 offset:4096
	s_waitcnt lgkmcnt(0)
	v_mfma_f32_32x32x16_bf16 v[48:63], v[66:69], v[70:73], v[48:63]
	v_mfma_f32_32x32x16_bf16 v[32:47], v[66:69], v[74:77], v[32:47]
	ds_read_b128 v[66:69], v84 offset:20480
	s_waitcnt lgkmcnt(0)
	v_mfma_f32_32x32x16_bf16 v[16:31], v[66:69], v[70:73], v[16:31]
	v_mfma_f32_32x32x16_bf16 v[0:15], v[66:69], v[74:77], v[0:15]
	ds_read_b128 v[66:69], v82 offset:16384
	v_add_u32_e32 v74, s0, v81
	ds_read_b128 v[70:73], v74
	ds_read_b128 v[74:77], v74 offset:4096
	s_waitcnt lgkmcnt(0)
	v_mfma_f32_32x32x16_bf16 v[48:63], v[66:69], v[70:73], v[48:63]
	v_mfma_f32_32x32x16_bf16 v[32:47], v[66:69], v[74:77], v[32:47]
	ds_read_b128 v[66:69], v82 offset:20480
	s_waitcnt lgkmcnt(0)
	v_mfma_f32_32x32x16_bf16 v[16:31], v[66:69], v[70:73], v[16:31]
	v_mfma_f32_32x32x16_bf16 v[0:15], v[66:69], v[74:77], v[0:15]
	ds_read_b128 v[66:69], v80 offset:16384
	v_add_u32_e32 v74, s0, v79
	ds_read_b128 v[70:73], v74
	ds_read_b128 v[74:77], v74 offset:4096
	s_waitcnt lgkmcnt(0)
	v_mfma_f32_32x32x16_bf16 v[48:63], v[66:69], v[70:73], v[48:63]
	v_mfma_f32_32x32x16_bf16 v[32:47], v[66:69], v[74:77], v[32:47]
	ds_read_b128 v[66:69], v80 offset:20480
	s_waitcnt vmcnt(0) lgkmcnt(0)
	s_barrier
	s_waitcnt lgkmcnt(0)
	v_mfma_f32_32x32x16_bf16 v[16:31], v[66:69], v[70:73], v[16:31]
	v_mfma_f32_32x32x16_bf16 v[0:15], v[66:69], v[74:77], v[0:15]
